# wave 7 of the chunk task no longer waits for the next-next task beta/decay loads inside stage D: they land in spare registers and are copied one task later
# baseline (speedup 1.0000x reference)
.LBB0_592:
	s_waitcnt lgkmcnt(0)
	s_barrier
	s_and_b64 vcc, exec, s[20:21]
	s_cbranch_vccnz .LBB0_770
	v_max_i32_e32 v1, 0x400, v88
	v_sub_u32_e32 v1, v1, v88
	v_add_u32_e32 v1, 0x1ff, v1
	s_movk_i32 s57, 0x1ff
	v_lshrrev_b32_e32 v2, 9, v1
	v_add_u32_e32 v3, 1, v2
	v_add_u32_e32 v2, -1, v2
	v_cmp_lt_u32_e64 s[4:5], s57, v1
	s_load_dwordx2 s[50:51], s[0:1], 0x38
	s_load_dwordx2 s[52:53], s[0:1], 0x80
	s_load_dwordx4 s[36:39], s[0:1], 0xa0
	s_load_dwordx4 s[40:43], s[0:1], 0xd0
	v_lshrrev_b32_e32 v4, 1, v2
	v_writelane_b32 v230, s4, 0
	v_add_u32_e32 v4, 1, v4
	v_and_b32_e32 v111, 3, v4
	v_writelane_b32 v230, s5, 1
	v_cmp_lt_u32_e64 s[4:5], 5, v2
	v_and_b32_e32 v0, 0x7f, v88
	v_and_b32_e32 v1, 0xfffffe, v3
	v_writelane_b32 v230, s4, 2
	v_lshlrev_b32_e32 v113, 2, v88
	s_movk_i32 s3, 0x600
	v_writelane_b32 v230, s5, 3
	v_cmp_ne_u32_e64 s[4:5], 0, v111
	v_mov_b32_e32 v79, 0
	v_lshl_add_u32 v110, v1, 9, v88
	v_writelane_b32 v230, s4, 4
	v_lshlrev_b32_e32 v90, 2, v0
	v_mbcnt_lo_u32_b32 v0, -1, 0
	v_writelane_b32 v230, s5, 5
	v_cmp_ne_u32_e64 s[4:5], v3, v1
	v_add_u32_e32 v1, 0, v113
	s_mov_b32 s35, s86
	v_cmp_gt_i32_e64 s[28:29], s3, v88
	s_mov_b32 s3, -1
	v_add_u32_e32 v89, 0x200, v88
	v_and_b32_e32 v112, -4, v4
	s_mov_b32 s55, 0
	v_writelane_b32 v230, s4, 6
	v_add_u32_e32 v114, 0x1fb00, v1
	v_add_u32_e32 v115, 0x20300, v1
	s_mov_b64 s[14:15], 0
	s_movk_i32 s76, 0x1000
	s_mov_b32 s77, 0x1f800
	s_mov_b32 s78, 0x11200
	s_movk_i32 s79, 0x310
	s_movk_i32 s80, 0x110
	s_movk_i32 s81, 0x1800
	s_add_i32 s82, 0, 0x15600
	s_add_i32 s83, 0, 0xce00
	s_mov_b32 s56, 0xbfb8aa3b
	s_mov_b32 s84, 0x800000
	s_mov_b32 s85, 0x2aaaaaab
	s_movk_i32 s86, 0x180
	s_movk_i32 s87, 0x3000
	s_add_i32 s88, 0, 0xc400
	s_movk_i32 s89, 0x1100
	s_add_i32 s90, 0, 0x1d000
	s_add_i32 s91, 0, 0x19a00
	s_movk_i32 s92, 0xef00
	s_movk_i32 s93, 0x50
	s_movk_i32 s94, 0x440
	s_add_i32 s95, 0, 0x1e400
	v_mbcnt_hi_u32_b32 v116, -1, v0
	s_add_i32 s96, 0, 0x1da00
	v_mov_b32_e32 v92, v90
	v_mov_b32_e32 v93, v79
	v_mov_b32_e32 v117, 0x3db504f3
	v_mov_b32_e32 v132, v79
	v_mov_b32_e32 v133, v79
	s_mov_b32 s97, 0
	s_mov_b32 s58, s2
	v_writelane_b32 v230, s5, 7
	v_mov_b32_e32 v250, v72
	v_mov_b32_e32 v251, v73
	s_branch .LBB0_595

.LBB0_753:
	v_and_b32_e32 v0, 0xffffffc0, v4
	s_movk_i32 s11, 0x1c0
	v_cmp_eq_u32_e32 vcc, s11, v0
	s_and_saveexec_b64 s[12:13], vcc
	s_cbranch_execz .LBB0_757
	v_and_b32_e32 v1, 63, v4
	s_andn2_b64 vcc, exec, s[66:67]
	v_mov_b32_e32 v72, v250
	v_mov_b32_e32 v73, v251
	s_cbranch_vccnz .LBB0_756
	v_lshl_or_b32 v2, s10, 6, v1
	v_ashrrev_i32_e32 v3, 31, v2
	v_lshlrev_b64 v[2:3], 6, v[2:3]
	v_lshl_add_u64 v[2:3], s[40:41], 0, v[2:3]
	s_lshl_b32 s54, s59, 2
	v_lshl_add_u64 v[2:3], v[2:3], 0, s[54:55]
	global_load_dword v250, v[2:3], off offset:32
	s_nop 0
	global_load_dword v251, v[2:3], off
.LBB0_756:
	v_add_u32_e32 v3, -1, v116
	v_cmp_lt_i32_e32 vcc, v3, v96
	v_add_u32_e32 v4, -2, v116
	v_add_u32_e32 v5, -4, v116
	v_cndmask_b32_e32 v3, v3, v116, vcc
	v_lshlrev_b32_e32 v3, 2, v3
	ds_bpermute_b32 v3, v3, v72
	v_cmp_eq_u32_e32 vcc, 0, v1
	s_and_b64 s[10:11], s[60:61], exec
	s_cselect_b32 s10, 0x21300, s77
	s_add_i32 s10, s10, 0
	s_waitcnt lgkmcnt(0)
	v_add_f32_e32 v3, v72, v3
	v_cndmask_b32_e32 v3, v3, v72, vcc
	v_cmp_lt_i32_e32 vcc, v4, v96
	v_cndmask_b32_e32 v4, v4, v116, vcc
	v_lshlrev_b32_e32 v4, 2, v4
	ds_bpermute_b32 v4, v4, v3
	v_cmp_gt_u32_e32 vcc, 2, v1
	s_waitcnt lgkmcnt(0)
	v_add_f32_e32 v4, v3, v4
	v_cndmask_b32_e32 v3, v4, v3, vcc
	v_cmp_lt_i32_e32 vcc, v5, v96
	s_nop 1
	v_cndmask_b32_e32 v4, v5, v116, vcc
	v_lshlrev_b32_e32 v4, 2, v4
	ds_bpermute_b32 v4, v4, v3
	v_cmp_gt_u32_e32 vcc, 4, v1
	s_waitcnt lgkmcnt(0)
	v_add_f32_e32 v4, v3, v4
	v_cndmask_b32_e32 v3, v4, v3, vcc
	v_add_u32_e32 v4, -8, v116
	v_cmp_lt_i32_e32 vcc, v4, v96
	s_nop 1
	v_cndmask_b32_e32 v4, v4, v116, vcc
	v_lshlrev_b32_e32 v4, 2, v4
	ds_bpermute_b32 v4, v4, v3
	v_cmp_gt_u32_e32 vcc, 8, v1
	s_waitcnt lgkmcnt(0)
	v_add_f32_e32 v4, v3, v4
	v_cndmask_b32_e32 v3, v4, v3, vcc
	v_add_u32_e32 v4, -16, v116
	v_cmp_lt_i32_e32 vcc, v4, v96
	s_nop 1
	v_cndmask_b32_e32 v4, v4, v116, vcc
	v_lshlrev_b32_e32 v4, 2, v4
	ds_bpermute_b32 v4, v4, v3
	v_cmp_gt_u32_e32 vcc, 16, v1
	s_waitcnt lgkmcnt(0)
	v_add_f32_e32 v4, v3, v4
	v_cndmask_b32_e32 v3, v4, v3, vcc
	v_subrev_u32_e32 v4, 32, v116
	v_cmp_lt_i32_e32 vcc, v4, v96
	s_nop 1
	v_cndmask_b32_e32 v4, v4, v116, vcc
	v_lshlrev_b32_e32 v4, 2, v4
	ds_bpermute_b32 v4, v4, v3
	v_cmp_gt_u32_e32 vcc, 32, v1
	v_lshl_add_u32 v1, v1, 2, s10
	s_waitcnt lgkmcnt(0)
	v_add_f32_e32 v4, v3, v4
	v_cndmask_b32_e32 v3, v4, v3, vcc
	v_mul_f32_e32 v4, 0x3fb8aa3b, v3
	v_exp_f32_e32 v4, v4
	ds_write2st64_b32 v1, v3, v73 offset1:1
	v_mul_f32_e32 v3, v73, v4
	ds_write_b32 v1, v3 offset:512
